# P7b prologue: the 8 sequential load round trips of the |qn_g|,|kn_g| max loop collapsed into 2 batches
# baseline (speedup 1.0000x reference)
; __global__ void __launch_bounds__(512, 2) mega_fwd(Params p) {
;     ...
;         {
;             float gq = 0.f, gk = 0.f;
;             for (int i = 0; i < 64; ++i) { gq = fmaxf(gq, fabsf(p.qn_g[i])); gk = fmaxf(gk, fabsf(p.kn_g[i])); }
;             const float mb = 8.f * gq * gk * 1.4426950408889634f;
;             for (int i = wave * 64 + lane8; i < 8 * 513; i += 512) bl[i] = p.rel_bias[i] * 1.4426950408889634f - mb;
;         }
.LBB0_1000:
	global_load_dwordx4 v[4:7], v0, s[62:63] offset:16
	global_load_dwordx4 v[10:13], v0, s[62:63]
	global_load_dwordx4 v[14:17], v0, s[64:65]
	global_load_dwordx4 v[18:21], v0, s[64:65] offset:16
	global_load_dwordx4 v[22:25], v0, s[62:63] offset:48
	global_load_dwordx4 v[26:29], v0, s[62:63] offset:32
	global_load_dwordx4 v[30:33], v0, s[64:65] offset:32
	global_load_dwordx4 v[34:37], v0, s[64:65] offset:48
	global_load_dwordx4 v[38:41], v0, s[62:63] offset:80
	global_load_dwordx4 v[42:45], v0, s[62:63] offset:64
	global_load_dwordx4 v[46:49], v0, s[64:65] offset:64
	global_load_dwordx4 v[50:53], v0, s[64:65] offset:80
	global_load_dwordx4 v[54:57], v0, s[62:63] offset:112
	global_load_dwordx4 v[58:61], v0, s[62:63] offset:96
	global_load_dwordx4 v[62:65], v0, s[64:65] offset:96
	global_load_dwordx4 v[66:69], v0, s[64:65] offset:112
	global_load_dwordx4 v[70:73], v0, s[62:63] offset:144
	global_load_dwordx4 v[74:77], v0, s[62:63] offset:128
	global_load_dwordx4 v[78:81], v0, s[64:65] offset:128
	global_load_dwordx4 v[82:85], v0, s[64:65] offset:144
	s_waitcnt vmcnt(0)
	v_max3_f32 v1, v1, |v10|, |v11|
	v_max3_f32 v1, v1, |v12|, |v13|
	v_max3_f32 v2, v2, |v14|, |v15|
	v_max3_f32 v2, v2, |v16|, |v17|
	v_max3_f32 v1, v1, |v4|, |v5|
	v_max3_f32 v2, v2, |v18|, |v19|
	v_max3_f32 v1, v1, |v6|, |v7|
	v_max3_f32 v2, v2, |v20|, |v21|
	v_max3_f32 v1, v1, |v26|, |v27|
	v_max3_f32 v1, v1, |v28|, |v29|
	v_max3_f32 v2, v2, |v30|, |v31|
	v_max3_f32 v2, v2, |v32|, |v33|
	v_max3_f32 v1, v1, |v22|, |v23|
	v_max3_f32 v2, v2, |v34|, |v35|
	v_max3_f32 v1, v1, |v24|, |v25|
	v_max3_f32 v2, v2, |v36|, |v37|
	v_max3_f32 v1, v1, |v42|, |v43|
	v_max3_f32 v1, v1, |v44|, |v45|
	v_max3_f32 v2, v2, |v46|, |v47|
	v_max3_f32 v2, v2, |v48|, |v49|
	v_max3_f32 v1, v1, |v38|, |v39|
	v_max3_f32 v2, v2, |v50|, |v51|
	v_max3_f32 v1, v1, |v40|, |v41|
	v_max3_f32 v2, v2, |v52|, |v53|
	v_max3_f32 v1, v1, |v58|, |v59|
	v_max3_f32 v1, v1, |v60|, |v61|
	v_max3_f32 v2, v2, |v62|, |v63|
	v_max3_f32 v2, v2, |v64|, |v65|
	v_max3_f32 v1, v1, |v54|, |v55|
	v_max3_f32 v2, v2, |v66|, |v67|
	v_max3_f32 v1, v1, |v56|, |v57|
	v_max3_f32 v2, v2, |v68|, |v69|
	v_max3_f32 v1, v1, |v74|, |v75|
	v_max3_f32 v1, v1, |v76|, |v77|
	v_max3_f32 v2, v2, |v78|, |v79|
	v_max3_f32 v2, v2, |v80|, |v81|
	v_max3_f32 v1, v1, |v70|, |v71|
	v_max3_f32 v2, v2, |v82|, |v83|
	v_max3_f32 v1, v1, |v72|, |v73|
	v_max3_f32 v2, v2, |v84|, |v85|
	global_load_dwordx4 v[4:7], v0, s[62:63] offset:176
	global_load_dwordx4 v[10:13], v0, s[62:63] offset:160
	global_load_dwordx4 v[14:17], v0, s[64:65] offset:160
	global_load_dwordx4 v[18:21], v0, s[64:65] offset:176
	global_load_dwordx4 v[22:25], v0, s[62:63] offset:208
	global_load_dwordx4 v[26:29], v0, s[62:63] offset:192
	global_load_dwordx4 v[30:33], v0, s[64:65] offset:192
	global_load_dwordx4 v[34:37], v0, s[64:65] offset:208
	global_load_dwordx4 v[38:41], v0, s[62:63] offset:240
	global_load_dwordx4 v[42:45], v0, s[62:63] offset:224
	global_load_dwordx4 v[46:49], v0, s[64:65] offset:224
	global_load_dwordx4 v[50:53], v0, s[64:65] offset:240
	s_waitcnt vmcnt(0)
	v_max3_f32 v1, v1, |v10|, |v11|
	v_max3_f32 v1, v1, |v12|, |v13|
	v_max3_f32 v2, v2, |v14|, |v15|
	v_max3_f32 v2, v2, |v16|, |v17|
	v_max3_f32 v1, v1, |v4|, |v5|
	v_max3_f32 v2, v2, |v18|, |v19|
	v_max3_f32 v1, v1, |v6|, |v7|
	v_max3_f32 v2, v2, |v20|, |v21|
	v_max3_f32 v1, v1, |v26|, |v27|
	v_max3_f32 v1, v1, |v28|, |v29|
	v_max3_f32 v2, v2, |v30|, |v31|
	v_max3_f32 v2, v2, |v32|, |v33|
	v_max3_f32 v1, v1, |v22|, |v23|
	v_max3_f32 v2, v2, |v34|, |v35|
	v_max3_f32 v1, v1, |v24|, |v25|
	v_max3_f32 v2, v2, |v36|, |v37|
	v_max3_f32 v1, v1, |v42|, |v43|
	v_max3_f32 v1, v1, |v44|, |v45|
	v_max3_f32 v2, v2, |v46|, |v47|
	v_max3_f32 v2, v2, |v48|, |v49|
	v_max3_f32 v1, v1, |v38|, |v39|
	v_max3_f32 v2, v2, |v50|, |v51|
	v_max3_f32 v1, v1, |v40|, |v41|
	v_max3_f32 v2, v2, |v52|, |v53|
	v_add_u32_e32 v0, s86, v8
	s_movk_i32 s0, 0x1008
	v_cmp_gt_i32_e32 vcc, s0, v0
	s_and_saveexec_b64 s[0:1], vcc
	v_readlane_b32 s14, v244, 29
	v_readlane_b32 s15, v244, 30
	s_cbranch_execz .LBB0_1014
	v_mul_f32_e32 v1, 0x41000000, v1
	v_mul_f32_e32 v1, v2, v1
	v_mul_f32_e32 v2, 0x3fb8aa3b, v1
	v_max_i32_e32 v1, 0xe08, v0
	v_sub_u32_e32 v1, v1, v0
	s_movk_i32 s4, 0x1ff
	v_add_u32_e32 v1, 0x1ff, v1
	v_cmp_lt_u32_e32 vcc, s4, v1
	s_mov_b64 s[8:9], -1
	v_mov_b32_e32 v6, v0
	s_and_saveexec_b64 s[4:5], vcc
	s_cbranch_execz .LBB0_1011
	v_lshrrev_b32_e32 v6, 9, v1
	v_add_u32_e32 v4, -1, v6
	v_add_u32_e32 v1, 0x200, v0
	v_lshrrev_b32_e32 v5, 1, v4
	v_mov_b32_e32 v3, v2
	v_add_u32_e32 v7, 1, v5
	v_cmp_lt_u32_e32 vcc, 13, v4
	v_mov_b32_e32 v11, 0
	v_mov_b64_e32 v[4:5], v[0:1]
	s_and_saveexec_b64 s[8:9], vcc
	s_cbranch_execz .LBB0_1007
	s_lshl_b32 s10, s69, 8
	s_add_i32 s10, s10, 0
	v_and_b32_e32 v9, -8, v7
	s_mov_b32 s13, 0
	v_lshl_add_u32 v10, v8, 2, s10
	s_mov_b64 s[10:11], 0
	s_mov_b32 s12, 0x3fb8aa3b
	v_mov_b64_e32 v[4:5], v[0:1]
